# v64 variant: P5 early SSP loads issued after the last iteration's SP2 DMA (never forced by a K-loop wait), last-iteration waits 14/14/14
# speedup vs baseline: 1.0011x; 1.0011x over previous
; #define PG8_STAGE(bufoff, gbase, voff) do { _Pragma("unroll") for (int _i = 0; _i < 2; ++_i) \
;         __builtin_amdgcn_global_load_lds((const unsigned*)((const char*)(gbase) + (voff)[_i]), (PG8_LAS unsigned*)(lds + (bufoff) + ldsw + _i * 8192), 16, 0, 0); } while (0)
; #define PG8_LDA(dst, b, h) do { _Pragma("unroll") for (int m = 0; m < 4; ++m) _Pragma("unroll") for (int k = 0; k < 2; ++k) dst[m][k] = *(const PG8_LAS bf16x8*)(lds + PG8_SA(b, h) + aoff + m * 2048 + k * 1024); } while (0)
; #define PG8_MMA(ai, bj, At, Bt) do { __builtin_amdgcn_s_setprio(1); _Pragma("unroll") for (int m = 0; m < 4; ++m) _Pragma("unroll") for (int n = 0; n < 2; ++n) _Pragma("unroll") for (int k = 0; k < 2; ++k) \
;         acc[ai][bj][m][n] = __builtin_amdgcn_mfma_f32_16x16x32_bf16(Bt[n][k], At[m][k], acc[ai][bj][m][n], 0, 0, 0); __builtin_amdgcn_s_setprio(0); } while (0)
; #define PG8_WAIT_V(n) asm volatile("s_waitcnt vmcnt(" #n ")" ::: "memory")
; #define PG8_WAIT_L(n) asm volatile("s_waitcnt lgkmcnt(" #n ")" ::: "memory")
; #define PG8_BAR __builtin_amdgcn_s_barrier()
; #define PG8_SCHED __builtin_amdgcn_sched_barrier(0)
; template <class Epi, class Sched, bool ALIGN_EPI = false, bool SP2 = false>
; __device__ __forceinline__ void gemm_phase(PG8_LAS unsigned char* lds, const Gemm g, const Sched& S, const Epi& E) {
;     ...
;             PG8_WAIT_V(8); PG8_WAIT_L(0); PG8_BAR; PG8_MMA(0, 0, At, B0); PG8_MMA(0, 1, At, B1); PG8_BAR; PG8_SCHED;
;             PG8_LDA(At, 0, 1); PG8_STAGE(PG8_SB(0, 0), b2, voffB); PG8_STAGE(PG8_SB(0, 1), b2 + hstep, voffB); PG8_STAGE(PG8_SA(0, 0), a2, voffA);
.Lrj_P5_0:
	s_waitcnt lgkmcnt(0)
	s_barrier
	s_setprio 1
	s_waitcnt lgkmcnt(0)
	v_mfma_f32_16x16x32_bf16 v[124:127], v[144:147], v[184:187], v[124:127]
	v_mfma_f32_16x16x32_bf16 v[120:123], v[160:163], v[184:187], v[120:123]
	v_mfma_f32_16x16x32_bf16 v[108:111], v[144:147], v[192:195], v[108:111]
	v_mfma_f32_16x16x32_bf16 v[104:107], v[160:163], v[192:195], v[104:107]
	v_mfma_f32_16x16x32_bf16 v[92:95], v[144:147], v[200:203], v[92:95]
	v_mfma_f32_16x16x32_bf16 v[88:91], v[160:163], v[200:203], v[88:91]
	v_mfma_f32_16x16x32_bf16 v[76:79], v[144:147], v[208:211], v[76:79]
	v_mfma_f32_16x16x32_bf16 v[72:75], v[160:163], v[208:211], v[72:75]
	v_mfma_f32_16x16x32_bf16 v[124:127], v[156:159], v[188:191], v[124:127]
	v_mfma_f32_16x16x32_bf16 v[120:123], v[164:167], v[188:191], v[120:123]
	v_mfma_f32_16x16x32_bf16 v[108:111], v[156:159], v[196:199], v[108:111]
	v_mfma_f32_16x16x32_bf16 v[104:107], v[164:167], v[196:199], v[104:107]
	v_mfma_f32_16x16x32_bf16 v[92:95], v[156:159], v[204:207], v[92:95]
	v_mfma_f32_16x16x32_bf16 v[88:91], v[164:167], v[204:207], v[88:91]
	v_mfma_f32_16x16x32_bf16 v[76:79], v[156:159], v[212:215], v[76:79]
	v_mfma_f32_16x16x32_bf16 v[72:75], v[164:167], v[212:215], v[72:75]
	s_setprio 0
	s_setprio 1
	v_mfma_f32_16x16x32_bf16 v[116:119], v[168:171], v[184:187], v[116:119]
	v_mfma_f32_16x16x32_bf16 v[112:115], v[176:179], v[184:187], v[112:115]
	v_mfma_f32_16x16x32_bf16 v[100:103], v[168:171], v[192:195], v[100:103]
	v_mfma_f32_16x16x32_bf16 v[96:99], v[176:179], v[192:195], v[96:99]
	v_mfma_f32_16x16x32_bf16 v[84:87], v[168:171], v[200:203], v[84:87]
	v_mfma_f32_16x16x32_bf16 v[80:83], v[176:179], v[200:203], v[80:83]
	v_mfma_f32_16x16x32_bf16 v[68:71], v[168:171], v[208:211], v[68:71]
	v_mfma_f32_16x16x32_bf16 v[64:67], v[176:179], v[208:211], v[64:67]
	v_mfma_f32_16x16x32_bf16 v[116:119], v[172:175], v[188:191], v[116:119]
	v_mfma_f32_16x16x32_bf16 v[112:115], v[180:183], v[188:191], v[112:115]
	v_mfma_f32_16x16x32_bf16 v[100:103], v[172:175], v[196:199], v[100:103]
	v_mfma_f32_16x16x32_bf16 v[96:99], v[180:183], v[196:199], v[96:99]
	v_mfma_f32_16x16x32_bf16 v[84:87], v[172:175], v[204:207], v[84:87]
	v_mfma_f32_16x16x32_bf16 v[80:83], v[180:183], v[204:207], v[80:83]
	v_mfma_f32_16x16x32_bf16 v[68:71], v[172:175], v[212:215], v[68:71]
	v_mfma_f32_16x16x32_bf16 v[64:67], v[180:183], v[212:215], v[64:67]
	s_setprio 0
	s_barrier
	s_add_i32 s66, s52, s39
	v_lshl_add_u64 v[216:217], s[34:35], 0, v[132:133]
	s_mov_b32 m0, s66
	ds_read_b128 v[184:187], v153 offset:16384
	ds_read_b128 v[188:191], v153 offset:17408
	ds_read_b128 v[192:195], v153 offset:18432
	ds_read_b128 v[196:199], v153 offset:19456
	ds_read_b128 v[200:203], v153 offset:20480
	ds_read_b128 v[204:207], v153 offset:21504
	ds_read_b128 v[208:211], v153 offset:22528
	ds_read_b128 v[212:215], v153 offset:23552
	global_load_lds_dwordx4 v[216:217], off
	s_add_i32 m0, s66, 0x2000
	s_add_u32 s66, s34, 0x40000
	v_lshl_add_u64 v[218:219], s[34:35], 0, v[128:129]
	s_addc_u32 s67, s35, 0
	s_add_i32 s68, s53, s39
	global_load_lds_dwordx4 v[218:219], off
	v_lshl_add_u64 v[220:221], s[66:67], 0, v[132:133]
	s_mov_b32 m0, s68
	v_lshl_add_u64 v[222:223], s[36:37], 0, v[130:131]
	global_load_lds_dwordx4 v[220:221], off
	v_lshl_add_u64 v[220:221], s[66:67], 0, v[128:129]
	s_add_i32 m0, s68, 0x2000
	s_nop 0
	global_load_lds_dwordx4 v[220:221], off
	v_lshl_add_u64 v[220:221], s[36:37], 0, v[134:135]
	s_mov_b32 m0, s29
	s_nop 0
	global_load_lds_dwordx4 v[220:221], off
	s_mov_b32 m0, s42
	s_nop 0
	global_load_lds_dwordx4 v[222:223], off
	s_cmp_eq_u32 s65, 12
	s_cbranch_scc0 .Lessp_skip
	v_lshl_add_u32 v252, s28, 8, v148
	v_bfe_u32 v253, v226, 4, 2
	v_lshlrev_b32_e32 v252, 6, v252
	v_lshl_add_u32 v252, v253, 4, v252
	v_add_u32_e32 v253, 0x2000, v252
	global_load_dwordx4 v[228:231], v252, s[12:13]
	global_load_dwordx4 v[232:235], v252, s[12:13] offset:1024
	global_load_dwordx4 v[236:239], v252, s[12:13] offset:2048
	global_load_dwordx4 v[240:243], v252, s[12:13] offset:3072
	global_load_dwordx4 v[244:247], v253, s[12:13]
	global_load_dwordx4 v[248:251], v253, s[12:13] offset:1024
.Lessp_skip:
	s_cmp_eq_u32 s99, 1
	s_cbranch_scc1 .Lrw_P5_1
	s_cmp_eq_u32 s65, 12
	s_cbranch_scc1 .Lw2l_P5
	s_waitcnt vmcnt(8)
	s_branch .Lrj_P5_1

; #define PG8_STAGE(bufoff, gbase, voff) do { _Pragma("unroll") for (int _i = 0; _i < 2; ++_i) \
;         __builtin_amdgcn_global_load_lds((const unsigned*)((const char*)(gbase) + (voff)[_i]), (PG8_LAS unsigned*)(lds + (bufoff) + ldsw + _i * 8192), 16, 0, 0); } while (0)
; #define PG8_LDA(dst, b, h) do { _Pragma("unroll") for (int m = 0; m < 4; ++m) _Pragma("unroll") for (int k = 0; k < 2; ++k) dst[m][k] = *(const PG8_LAS bf16x8*)(lds + PG8_SA(b, h) + aoff + m * 2048 + k * 1024); } while (0)
; #define PG8_MMA(ai, bj, At, Bt) do { __builtin_amdgcn_s_setprio(1); _Pragma("unroll") for (int m = 0; m < 4; ++m) _Pragma("unroll") for (int n = 0; n < 2; ++n) _Pragma("unroll") for (int k = 0; k < 2; ++k) \
;         acc[ai][bj][m][n] = __builtin_amdgcn_mfma_f32_16x16x32_bf16(Bt[n][k], At[m][k], acc[ai][bj][m][n], 0, 0, 0); __builtin_amdgcn_s_setprio(0); } while (0)
; #define PG8_WAIT_V(n) asm volatile("s_waitcnt vmcnt(" #n ")" ::: "memory")
; #define PG8_WAIT_L(n) asm volatile("s_waitcnt lgkmcnt(" #n ")" ::: "memory")
; #define PG8_BAR __builtin_amdgcn_s_barrier()
; #define PG8_SCHED __builtin_amdgcn_sched_barrier(0)
; template <class Epi, class Sched, bool ALIGN_EPI = false, bool SP2 = false>
; __device__ __forceinline__ void gemm_phase(PG8_LAS unsigned char* lds, const Gemm g, const Sched& S, const Epi& E) {
;     ...
;             PG8_WAIT_V(8); PG8_WAIT_L(0); PG8_BAR; PG8_MMA(0, 0, At, B0); PG8_MMA(0, 1, At, B1); PG8_BAR; PG8_SCHED;
;             PG8_LDA(At, 1, 1); PG8_STAGE(PG8_SB(1, 0), b3, voffB); PG8_STAGE(PG8_SB(1, 1), b3 + hstep, voffB); PG8_STAGE(PG8_SA(1, 0), a3, voffA);
.Lx2d_P5:
	s_waitcnt lgkmcnt(0)
	s_barrier
	s_setprio 1
	s_waitcnt lgkmcnt(0)
	v_mfma_f32_16x16x32_bf16 v[124:127], v[144:147], v[184:187], v[124:127]
	v_mfma_f32_16x16x32_bf16 v[120:123], v[160:163], v[184:187], v[120:123]
	v_mfma_f32_16x16x32_bf16 v[108:111], v[144:147], v[192:195], v[108:111]
	v_mfma_f32_16x16x32_bf16 v[104:107], v[160:163], v[192:195], v[104:107]
	v_mfma_f32_16x16x32_bf16 v[92:95], v[144:147], v[200:203], v[92:95]
	v_mfma_f32_16x16x32_bf16 v[88:91], v[160:163], v[200:203], v[88:91]
	v_mfma_f32_16x16x32_bf16 v[76:79], v[144:147], v[208:211], v[76:79]
	v_mfma_f32_16x16x32_bf16 v[72:75], v[160:163], v[208:211], v[72:75]
	v_mfma_f32_16x16x32_bf16 v[124:127], v[156:159], v[188:191], v[124:127]
	v_mfma_f32_16x16x32_bf16 v[120:123], v[164:167], v[188:191], v[120:123]
	v_mfma_f32_16x16x32_bf16 v[108:111], v[156:159], v[196:199], v[108:111]
	v_mfma_f32_16x16x32_bf16 v[104:107], v[164:167], v[196:199], v[104:107]
	v_mfma_f32_16x16x32_bf16 v[92:95], v[156:159], v[204:207], v[92:95]
	v_mfma_f32_16x16x32_bf16 v[88:91], v[164:167], v[204:207], v[88:91]
	v_mfma_f32_16x16x32_bf16 v[76:79], v[156:159], v[212:215], v[76:79]
	v_mfma_f32_16x16x32_bf16 v[72:75], v[164:167], v[212:215], v[72:75]
	s_setprio 0
	s_setprio 1
	v_mfma_f32_16x16x32_bf16 v[116:119], v[168:171], v[184:187], v[116:119]
	v_mfma_f32_16x16x32_bf16 v[112:115], v[176:179], v[184:187], v[112:115]
	v_mfma_f32_16x16x32_bf16 v[100:103], v[168:171], v[192:195], v[100:103]
	v_mfma_f32_16x16x32_bf16 v[96:99], v[176:179], v[192:195], v[96:99]
	v_mfma_f32_16x16x32_bf16 v[84:87], v[168:171], v[200:203], v[84:87]
	v_mfma_f32_16x16x32_bf16 v[80:83], v[176:179], v[200:203], v[80:83]
	v_mfma_f32_16x16x32_bf16 v[68:71], v[168:171], v[208:211], v[68:71]
	v_mfma_f32_16x16x32_bf16 v[64:67], v[176:179], v[208:211], v[64:67]
	v_mfma_f32_16x16x32_bf16 v[116:119], v[172:175], v[188:191], v[116:119]
	v_mfma_f32_16x16x32_bf16 v[112:115], v[180:183], v[188:191], v[112:115]
	v_mfma_f32_16x16x32_bf16 v[100:103], v[172:175], v[196:199], v[100:103]
	v_mfma_f32_16x16x32_bf16 v[96:99], v[180:183], v[196:199], v[96:99]
	v_mfma_f32_16x16x32_bf16 v[84:87], v[172:175], v[204:207], v[84:87]
	v_mfma_f32_16x16x32_bf16 v[80:83], v[180:183], v[204:207], v[80:83]
	v_mfma_f32_16x16x32_bf16 v[68:71], v[172:175], v[212:215], v[68:71]
	v_mfma_f32_16x16x32_bf16 v[64:67], v[180:183], v[212:215], v[64:67]
	s_setprio 0
	s_barrier
	s_add_i32 s36, s66, s39
	v_lshl_add_u64 v[216:217], v[216:217], 0, s[14:15]
	s_mov_b32 m0, s36
	ds_read_b128 v[184:187], v153 offset:49152
	ds_read_b128 v[188:191], v153 offset:50176
	ds_read_b128 v[192:195], v153 offset:51200
	ds_read_b128 v[196:199], v153 offset:52224
	ds_read_b128 v[200:203], v153 offset:53248
	ds_read_b128 v[204:207], v153 offset:54272
	ds_read_b128 v[208:211], v153 offset:55296
	ds_read_b128 v[212:215], v153 offset:56320
	global_load_lds_dwordx4 v[216:217], off
	s_add_i32 m0, s36, 0x2000
	s_add_u32 s34, s34, 0x40080
	v_lshl_add_u64 v[216:217], v[218:219], 0, s[14:15]
	s_addc_u32 s35, s35, 0
	s_add_i32 s36, s67, s39
	global_load_lds_dwordx4 v[216:217], off
	v_lshl_add_u64 v[216:217], s[34:35], 0, v[132:133]
	s_mov_b32 m0, s36
	s_nop 0
	global_load_lds_dwordx4 v[216:217], off
	v_lshl_add_u64 v[216:217], s[34:35], 0, v[128:129]
	s_add_i32 m0, s36, 0x2000
	s_nop 0
	global_load_lds_dwordx4 v[216:217], off
	v_lshl_add_u64 v[216:217], v[220:221], 0, s[14:15]
	s_mov_b32 m0, s49
	s_nop 0
	global_load_lds_dwordx4 v[216:217], off
	v_lshl_add_u64 v[216:217], v[222:223], 0, s[14:15]
	s_mov_b32 m0, s50
	s_nop 0
	global_load_lds_dwordx4 v[216:217], off
	s_cmp_eq_u32 s65, 12
	s_cbranch_scc1 .Lx3l_P5
	s_waitcnt vmcnt(8)
	s_branch .Lx3d_P5

; #define PG8_MMA(ai, bj, At, Bt) do { __builtin_amdgcn_s_setprio(1); _Pragma("unroll") for (int m = 0; m < 4; ++m) _Pragma("unroll") for (int n = 0; n < 2; ++n) _Pragma("unroll") for (int k = 0; k < 2; ++k) \
;         acc[ai][bj][m][n] = __builtin_amdgcn_mfma_f32_16x16x32_bf16(Bt[n][k], At[m][k], acc[ai][bj][m][n], 0, 0, 0); __builtin_amdgcn_s_setprio(0); } while (0)
; #define PG8_WAIT_V(n) asm volatile("s_waitcnt vmcnt(" #n ")" ::: "memory")
; #define PG8_WAIT_L(n) asm volatile("s_waitcnt lgkmcnt(" #n ")" ::: "memory")
; #define PG8_BAR __builtin_amdgcn_s_barrier()
; #define PG8_SCHED __builtin_amdgcn_sched_barrier(0)
; template <class Epi, class Sched, bool ALIGN_EPI = false, bool SP2 = false>
; __device__ __forceinline__ void gemm_phase(PG8_LAS unsigned char* lds, const Gemm g, const Sched& S, const Epi& E) {
;     ...
;             PG8_WAIT_V(8); PG8_WAIT_L(0); PG8_BAR; PG8_MMA(1, 0, At, B0); PG8_MMA(1, 1, At, B1); PG8_BAR; PG8_SCHED;
;     __device__ __forceinline__ void operator()(const f32x4 (&acc)[2][2][4][2], const Unit& u, int wr, int wc, int fr, int fq) const {
;     ...
;             for (int m = 0; m < 4; ++m) { const int row = rbase + ai * 128 + m * 16; const f32x4* sp = (const f32x4*)(SSP + (size_t)row * 16);
;                 const f32x4 s4 = (sp[0] + sp[1]) + (sp[2] + sp[3]); const float rstd = __builtin_amdgcn_rsqf(((s4[0] + s4[1]) + (s4[2] + s4[3])) * (1.0f / 1024.0f) + EPS);
.Lx3d_P5:
	s_waitcnt lgkmcnt(0)
	s_barrier
	s_setprio 1
	s_waitcnt lgkmcnt(0)
	v_mfma_f32_16x16x32_bf16 v[60:63], v[144:147], v[184:187], v[60:63]
	v_mfma_f32_16x16x32_bf16 v[56:59], v[160:163], v[184:187], v[56:59]
	v_mfma_f32_16x16x32_bf16 v[44:47], v[144:147], v[192:195], v[44:47]
	v_mfma_f32_16x16x32_bf16 v[40:43], v[160:163], v[192:195], v[40:43]
	v_mfma_f32_16x16x32_bf16 v[28:31], v[144:147], v[200:203], v[28:31]
	v_mfma_f32_16x16x32_bf16 v[24:27], v[160:163], v[200:203], v[24:27]
	v_mfma_f32_16x16x32_bf16 v[12:15], v[144:147], v[208:211], v[12:15]
	v_mfma_f32_16x16x32_bf16 v[8:11], v[160:163], v[208:211], v[8:11]
	v_mfma_f32_16x16x32_bf16 v[60:63], v[156:159], v[188:191], v[60:63]
	v_mfma_f32_16x16x32_bf16 v[56:59], v[164:167], v[188:191], v[56:59]
	v_mfma_f32_16x16x32_bf16 v[44:47], v[156:159], v[196:199], v[44:47]
	v_mfma_f32_16x16x32_bf16 v[40:43], v[164:167], v[196:199], v[40:43]
	v_mfma_f32_16x16x32_bf16 v[28:31], v[156:159], v[204:207], v[28:31]
	v_mfma_f32_16x16x32_bf16 v[24:27], v[164:167], v[204:207], v[24:27]
	v_mfma_f32_16x16x32_bf16 v[12:15], v[156:159], v[212:215], v[12:15]
	v_mfma_f32_16x16x32_bf16 v[8:11], v[164:167], v[212:215], v[8:11]
	s_setprio 0
	s_setprio 1
	v_mfma_f32_16x16x32_bf16 v[52:55], v[168:171], v[184:187], v[52:55]
	v_mfma_f32_16x16x32_bf16 v[48:51], v[176:179], v[184:187], v[48:51]
	v_mfma_f32_16x16x32_bf16 v[36:39], v[168:171], v[192:195], v[36:39]
	v_mfma_f32_16x16x32_bf16 v[32:35], v[176:179], v[192:195], v[32:35]
	v_mfma_f32_16x16x32_bf16 v[20:23], v[168:171], v[200:203], v[20:23]
	v_mfma_f32_16x16x32_bf16 v[16:19], v[176:179], v[200:203], v[16:19]
	v_mfma_f32_16x16x32_bf16 v[4:7], v[168:171], v[208:211], v[4:7]
	v_mfma_f32_16x16x32_bf16 v[0:3], v[176:179], v[208:211], v[0:3]
	v_mfma_f32_16x16x32_bf16 v[52:55], v[172:175], v[188:191], v[52:55]
	v_mfma_f32_16x16x32_bf16 v[48:51], v[180:183], v[188:191], v[48:51]
	v_mfma_f32_16x16x32_bf16 v[36:39], v[172:175], v[196:199], v[36:39]
	v_mfma_f32_16x16x32_bf16 v[32:35], v[180:183], v[196:199], v[32:35]
	v_mfma_f32_16x16x32_bf16 v[20:23], v[172:175], v[204:207], v[20:23]
	v_mfma_f32_16x16x32_bf16 v[16:19], v[180:183], v[204:207], v[16:19]
	v_mfma_f32_16x16x32_bf16 v[4:7], v[172:175], v[212:215], v[4:7]
	v_mfma_f32_16x16x32_bf16 v[0:3], v[180:183], v[212:215], v[0:3]
	s_setprio 0
	s_barrier
	s_mov_b32 s99, 0
	s_add_i32 s65, s65, 2
	s_add_u32 s30, s30, 0x100
	s_addc_u32 s31, s31, 0
	s_add_u32 s63, s63, 0x100
	s_addc_u32 s64, s64, 0
	s_cmp_gt_u32 s65, 13
	s_cbranch_scc0 .LBB0_1540
	v_lshl_add_u32 v146, s28, 8, v148
	v_ashrrev_i32_e32 v147, 31, v146
	v_lshlrev_b64 v[144:145], 6, v[146:147]
	v_lshl_add_u64 v[144:145], s[12:13], 0, v[144:145]
	v_bfe_u32 v156, v226, 4, 2
	v_lshlrev_b32_e32 v156, 4, v156
	v_mov_b32_e32 v157, 0
	v_lshl_add_u64 v[144:145], v[144:145], 0, v[156:157]
	s_mov_b64 s[98:99], 0x2000
	v_lshl_add_u64 v[222:223], v[144:145], 0, s[98:99]
	global_load_dwordx4 v[180:183], v[222:223], off offset:2048
	global_load_dwordx4 v[184:187], v[222:223], off offset:3072
	s_and_b64 vcc, exec, s[16:17]
	s_cbranch_vccz .LBB0_1543
	s_barrier
